# G2 context-row tiles also take a batched residual epilogue (f32 source and destination)
# baseline (speedup 1.0000x reference)
;     __device__ __forceinline__ void operator()(const f32x4 (&acc)[2][2][4][2], const Unit& u, int wr, int wc, int fr, int fq) const {
;     ...
;                     if (!lat) { b0 = *(const f32x4*)(baseC + off + bj * HALF); b1 = *(const f32x4*)(baseC + off + bj * HALF + 4); }
;                     else if (baseLf) { b0 = *(const f32x4*)(baseLf + off + bj * HALF); b1 = *(const f32x4*)(baseLf + off + bj * HALF + 4); }
;                     else { const u32x4 w = *(const u32x4*)(baseLb + off + bj * HALF);
;                         b0 = (f32x4){__builtin_bit_cast(float, w.x << 16), __builtin_bit_cast(float, w.x & 0xffff0000u), __builtin_bit_cast(float, w.y << 16), __builtin_bit_cast(float, w.y & 0xffff0000u)};
;                         b1 = (f32x4){__builtin_bit_cast(float, w.z << 16), __builtin_bit_cast(float, w.z & 0xffff0000u), __builtin_bit_cast(float, w.w << 16), __builtin_bit_cast(float, w.w & 0xffff0000u)}; }
;                     const f32x4 o0 = b0 + g[bj][0] * acc[ai][bj][m][0], o1 = b1 + g[bj][1] * acc[ai][bj][m][1];
;                     if (!lat) { *(f32x4*)(outC + off + bj * HALF) = o0; *(f32x4*)(outC + off + bj * HALF + 4) = o1; }
.Lep2_ctx:
	v_lshl_add_u64 v[168:169], v[166:167], 2, s[46:47]
	v_lshl_add_u64 v[164:165], v[166:167], 2, s[26:27]
	s_mov_b64 s[12:13], 0x10000
	s_mov_b64 s[14:15], 0x50000
	global_load_dwordx4 v[174:177], v[168:169], off
	global_load_dwordx4 v[178:181], v[168:169], off offset:16
	global_load_dwordx4 v[182:185], v[168:169], off offset:512
	global_load_dwordx4 v[186:189], v[168:169], off offset:528
	v_lshl_add_u64 v[168:169], v[168:169], 0, s[12:13]
	global_load_dwordx4 v[190:193], v[168:169], off
	global_load_dwordx4 v[194:197], v[168:169], off offset:16
	global_load_dwordx4 v[198:201], v[168:169], off offset:512
	global_load_dwordx4 v[202:205], v[168:169], off offset:528
	s_waitcnt vmcnt(6)
	v_pk_fma_f32 v[140:141], v[140:141], v[60:61], v[174:175]
	v_pk_fma_f32 v[142:143], v[142:143], v[62:63], v[176:177]
	v_pk_fma_f32 v[136:137], v[136:137], v[56:57], v[178:179]
	v_pk_fma_f32 v[138:139], v[138:139], v[58:59], v[180:181]
	v_lshl_add_u64 v[168:169], v[168:169], 0, s[12:13]
	global_load_dwordx4 v[174:177], v[168:169], off
	global_load_dwordx4 v[178:181], v[168:169], off offset:16
	s_waitcnt vmcnt(6)
	v_pk_fma_f32 v[132:133], v[132:133], v[44:45], v[182:183]
	v_pk_fma_f32 v[134:135], v[134:135], v[46:47], v[184:185]
	v_pk_fma_f32 v[128:129], v[128:129], v[40:41], v[186:187]
	v_pk_fma_f32 v[130:131], v[130:131], v[42:43], v[188:189]
	global_load_dwordx4 v[182:185], v[168:169], off offset:512
	global_load_dwordx4 v[186:189], v[168:169], off offset:528
	s_waitcnt vmcnt(6)
	v_pk_fma_f32 v[124:125], v[124:125], v[60:61], v[190:191]
	v_pk_fma_f32 v[126:127], v[126:127], v[62:63], v[192:193]
	v_pk_fma_f32 v[120:121], v[120:121], v[56:57], v[194:195]
	v_pk_fma_f32 v[122:123], v[122:123], v[58:59], v[196:197]
	v_lshl_add_u64 v[168:169], v[168:169], 0, s[12:13]
	global_load_dwordx4 v[190:193], v[168:169], off
	global_load_dwordx4 v[194:197], v[168:169], off offset:16
	s_waitcnt vmcnt(6)
	v_pk_fma_f32 v[116:117], v[116:117], v[44:45], v[198:199]
	v_pk_fma_f32 v[118:119], v[118:119], v[46:47], v[200:201]
	v_pk_fma_f32 v[112:113], v[112:113], v[40:41], v[202:203]
	v_pk_fma_f32 v[114:115], v[114:115], v[42:43], v[204:205]
	global_load_dwordx4 v[198:201], v[168:169], off offset:512
	global_load_dwordx4 v[202:205], v[168:169], off offset:528
	s_waitcnt vmcnt(6)
	v_pk_fma_f32 v[108:109], v[108:109], v[60:61], v[174:175]
	v_pk_fma_f32 v[110:111], v[110:111], v[62:63], v[176:177]
	v_pk_fma_f32 v[104:105], v[104:105], v[56:57], v[178:179]
	v_pk_fma_f32 v[106:107], v[106:107], v[58:59], v[180:181]
	v_lshl_add_u64 v[168:169], v[168:169], 0, s[14:15]
	global_load_dwordx4 v[174:177], v[168:169], off
	global_load_dwordx4 v[178:181], v[168:169], off offset:16
	s_waitcnt vmcnt(6)
	v_pk_fma_f32 v[100:101], v[100:101], v[44:45], v[182:183]
	v_pk_fma_f32 v[102:103], v[102:103], v[46:47], v[184:185]
	v_pk_fma_f32 v[96:97], v[96:97], v[40:41], v[186:187]
	v_pk_fma_f32 v[98:99], v[98:99], v[42:43], v[188:189]
	global_load_dwordx4 v[182:185], v[168:169], off offset:512
	global_load_dwordx4 v[186:189], v[168:169], off offset:528
	s_waitcnt vmcnt(6)
	v_pk_fma_f32 v[92:93], v[92:93], v[60:61], v[190:191]
	v_pk_fma_f32 v[94:95], v[94:95], v[62:63], v[192:193]
	v_pk_fma_f32 v[88:89], v[88:89], v[56:57], v[194:195]
	v_pk_fma_f32 v[90:91], v[90:91], v[58:59], v[196:197]
	v_lshl_add_u64 v[168:169], v[168:169], 0, s[12:13]
	global_load_dwordx4 v[190:193], v[168:169], off
	global_load_dwordx4 v[194:197], v[168:169], off offset:16
	s_waitcnt vmcnt(6)
	v_pk_fma_f32 v[84:85], v[84:85], v[44:45], v[198:199]
	v_pk_fma_f32 v[86:87], v[86:87], v[46:47], v[200:201]
	v_pk_fma_f32 v[80:81], v[80:81], v[40:41], v[202:203]
	v_pk_fma_f32 v[82:83], v[82:83], v[42:43], v[204:205]
	global_load_dwordx4 v[198:201], v[168:169], off offset:512
	global_load_dwordx4 v[202:205], v[168:169], off offset:528
	s_waitcnt vmcnt(6)
	v_pk_fma_f32 v[76:77], v[76:77], v[60:61], v[174:175]
	v_pk_fma_f32 v[78:79], v[78:79], v[62:63], v[176:177]
	v_pk_fma_f32 v[72:73], v[72:73], v[56:57], v[178:179]
	v_pk_fma_f32 v[74:75], v[74:75], v[58:59], v[180:181]
	v_lshl_add_u64 v[168:169], v[168:169], 0, s[12:13]
	global_load_dwordx4 v[174:177], v[168:169], off
	global_load_dwordx4 v[178:181], v[168:169], off offset:16
	s_waitcnt vmcnt(6)
; __device__ __forceinline__ unsigned cvt_pk_bf16(float lo, float hi) { unsigned r; asm volatile("v_cvt_pk_bf16_f32 %0, %1, %2" : "=v"(r) : "v"(lo), "v"(hi)); return r; }
;     __device__ __forceinline__ void operator()(const f32x4 (&acc)[2][2][4][2], const Unit& u, int wr, int wc, int fr, int fq) const {
;     ...
;                     if (!lat) { b0 = *(const f32x4*)(baseC + off + bj * HALF); b1 = *(const f32x4*)(baseC + off + bj * HALF + 4); }
;                     else if (baseLf) { b0 = *(const f32x4*)(baseLf + off + bj * HALF); b1 = *(const f32x4*)(baseLf + off + bj * HALF + 4); }
;                     else { const u32x4 w = *(const u32x4*)(baseLb + off + bj * HALF);
;                         b0 = (f32x4){__builtin_bit_cast(float, w.x << 16), __builtin_bit_cast(float, w.x & 0xffff0000u), __builtin_bit_cast(float, w.y << 16), __builtin_bit_cast(float, w.y & 0xffff0000u)};
;                         b1 = (f32x4){__builtin_bit_cast(float, w.z << 16), __builtin_bit_cast(float, w.z & 0xffff0000u), __builtin_bit_cast(float, w.w << 16), __builtin_bit_cast(float, w.w & 0xffff0000u)}; }
;                     const f32x4 o0 = b0 + g[bj][0] * acc[ai][bj][m][0], o1 = b1 + g[bj][1] * acc[ai][bj][m][1];
;                     if (!lat) { *(f32x4*)(outC + off + bj * HALF) = o0; *(f32x4*)(outC + off + bj * HALF + 4) = o1; }
;                     else { u32x4 w; w.x = cvt_pk_bf16(o0.x, o0.y); w.y = cvt_pk_bf16(o0.z, o0.w); w.z = cvt_pk_bf16(o1.x, o1.y); w.w = cvt_pk_bf16(o1.z, o1.w); *(u32x4*)(outL + off + bj * HALF) = w; }
;                 }
	v_pk_fma_f32 v[68:69], v[68:69], v[44:45], v[182:183]
	v_pk_fma_f32 v[70:71], v[70:71], v[46:47], v[184:185]
	v_pk_fma_f32 v[64:65], v[64:65], v[40:41], v[186:187]
	v_pk_fma_f32 v[66:67], v[66:67], v[42:43], v[188:189]
	global_load_dwordx4 v[182:185], v[168:169], off offset:512
	global_load_dwordx4 v[186:189], v[168:169], off offset:528
	s_waitcnt vmcnt(6)
	v_pk_fma_f32 v[52:53], v[52:53], v[60:61], v[190:191]
	v_pk_fma_f32 v[54:55], v[54:55], v[62:63], v[192:193]
	v_pk_fma_f32 v[48:49], v[48:49], v[56:57], v[194:195]
	v_pk_fma_f32 v[50:51], v[50:51], v[58:59], v[196:197]
	v_lshl_add_u64 v[168:169], v[168:169], 0, s[12:13]
	global_load_dwordx4 v[190:193], v[168:169], off
	global_load_dwordx4 v[194:197], v[168:169], off offset:16
	s_waitcnt vmcnt(6)
	v_pk_fma_f32 v[36:37], v[36:37], v[44:45], v[198:199]
	v_pk_fma_f32 v[38:39], v[38:39], v[46:47], v[200:201]
	v_pk_fma_f32 v[32:33], v[32:33], v[40:41], v[202:203]
	v_pk_fma_f32 v[34:35], v[34:35], v[42:43], v[204:205]
	global_load_dwordx4 v[198:201], v[168:169], off offset:512
	global_load_dwordx4 v[202:205], v[168:169], off offset:528
	s_waitcnt vmcnt(6)
	v_pk_fma_f32 v[28:29], v[28:29], v[60:61], v[174:175]
	v_pk_fma_f32 v[30:31], v[30:31], v[62:63], v[176:177]
	v_pk_fma_f32 v[24:25], v[24:25], v[56:57], v[178:179]
	v_pk_fma_f32 v[26:27], v[26:27], v[58:59], v[180:181]
	s_waitcnt vmcnt(4)
	v_pk_fma_f32 v[20:21], v[20:21], v[44:45], v[182:183]
	v_pk_fma_f32 v[22:23], v[22:23], v[46:47], v[184:185]
	v_pk_fma_f32 v[16:17], v[16:17], v[40:41], v[186:187]
	v_pk_fma_f32 v[18:19], v[18:19], v[42:43], v[188:189]
	s_waitcnt vmcnt(2)
	v_pk_fma_f32 v[12:13], v[12:13], v[60:61], v[190:191]
	v_pk_fma_f32 v[14:15], v[14:15], v[62:63], v[192:193]
	v_pk_fma_f32 v[8:9], v[8:9], v[56:57], v[194:195]
	v_pk_fma_f32 v[10:11], v[10:11], v[58:59], v[196:197]
	s_waitcnt vmcnt(0)
	v_pk_fma_f32 v[4:5], v[4:5], v[44:45], v[198:199]
	v_pk_fma_f32 v[6:7], v[6:7], v[46:47], v[200:201]
	v_pk_fma_f32 v[0:1], v[0:1], v[40:41], v[202:203]
	v_pk_fma_f32 v[2:3], v[2:3], v[42:43], v[204:205]
	global_store_dwordx4 v[164:165], v[140:143], off
	global_store_dwordx4 v[164:165], v[136:139], off offset:16
	global_store_dwordx4 v[164:165], v[132:135], off offset:512
	global_store_dwordx4 v[164:165], v[128:131], off offset:528
	v_lshl_add_u64 v[164:165], v[164:165], 0, s[12:13]
	global_store_dwordx4 v[164:165], v[124:127], off
	global_store_dwordx4 v[164:165], v[120:123], off offset:16
	global_store_dwordx4 v[164:165], v[116:119], off offset:512
	global_store_dwordx4 v[164:165], v[112:115], off offset:528
	v_lshl_add_u64 v[164:165], v[164:165], 0, s[12:13]
	global_store_dwordx4 v[164:165], v[108:111], off
	global_store_dwordx4 v[164:165], v[104:107], off offset:16
	global_store_dwordx4 v[164:165], v[100:103], off offset:512
	global_store_dwordx4 v[164:165], v[96:99], off offset:528
	v_lshl_add_u64 v[164:165], v[164:165], 0, s[12:13]
	global_store_dwordx4 v[164:165], v[92:95], off
	global_store_dwordx4 v[164:165], v[88:91], off offset:16
	global_store_dwordx4 v[164:165], v[84:87], off offset:512
	global_store_dwordx4 v[164:165], v[80:83], off offset:528
	v_lshl_add_u64 v[164:165], v[164:165], 0, s[14:15]
	global_store_dwordx4 v[164:165], v[76:79], off
	global_store_dwordx4 v[164:165], v[72:75], off offset:16
	global_store_dwordx4 v[164:165], v[68:71], off offset:512
	global_store_dwordx4 v[164:165], v[64:67], off offset:528
	v_lshl_add_u64 v[164:165], v[164:165], 0, s[12:13]
	global_store_dwordx4 v[164:165], v[52:55], off
	global_store_dwordx4 v[164:165], v[48:51], off offset:16
	global_store_dwordx4 v[164:165], v[36:39], off offset:512
	global_store_dwordx4 v[164:165], v[32:35], off offset:528
	v_lshl_add_u64 v[164:165], v[164:165], 0, s[12:13]
	global_store_dwordx4 v[164:165], v[28:31], off
	global_store_dwordx4 v[164:165], v[24:27], off offset:16
	global_store_dwordx4 v[164:165], v[20:23], off offset:512
	global_store_dwordx4 v[164:165], v[16:19], off offset:528
	v_lshl_add_u64 v[164:165], v[164:165], 0, s[12:13]
	global_store_dwordx4 v[164:165], v[12:15], off
	global_store_dwordx4 v[164:165], v[8:11], off offset:16
	global_store_dwordx4 v[164:165], v[4:7], off offset:512
	global_store_dwordx4 v[164:165], v[0:3], off offset:528
	s_mov_b64 s[40:41], -1
	s_mov_b64 s[48:49], -1
	s_branch .Lep2_join
